# spatial gating epilogue: eight u-tile loads issued up front with counted vmcnt(7) waits instead of eight serialized load/wait/store steps
# baseline (speedup 1.0000x reference)
; #define LAS __attribute__((address_space(3)))
; __device__ __forceinline__ u32x2 pack4(f32x4 v) { return (u32x2){pk2(v[0], v[1]), pk2(v[2], v[3])}; }
; __device__ __forceinline__ f32x4 unpack4(u32x2 w) { return (f32x4){bflo(w.x), bfhi(w.x), bflo(w.y), bfhi(w.y)}; }
; __device__ __forceinline__ void sg_unit(LAS unsigned char* lds, const bf16_t* P0, bf16_t* MIX, const float* lng, const float* lnb, const float* wsp, const float* bsp, int b, int nch, int g) {
;     ...
;     const int nks = ((16 * w + 15) >> 5) + 1;
;     for (int ks = 0; ks < nks; ++ks) { const bf16x8 bfrag = *(const LAS bf16x8*)(Wl + (16 * w + fr) * 136 + 32 * ks + 8 * fq);
; #pragma unroll
;         for (int mi = 0; mi < 8; ++mi) { typedef short v4s __attribute__((ext_vector_type(4)));
;             const LAS bf16_t* p_ = vnl + (32 * ks + 8 * fq + (fr >> 2)) * 136 + 16 * mi + 4 * (fr & 3);
;             const v4s lo_ = __builtin_amdgcn_ds_read_tr16_b64_v4i16((LAS v4s*)p_), hi_ = __builtin_amdgcn_ds_read_tr16_b64_v4i16((LAS v4s*)(p_ + 4 * 136));
;             const bf16x8 afrag = (bf16x8){lo_[0], lo_[1], lo_[2], lo_[3], hi_[0], hi_[1], hi_[2], hi_[3]};
;             acc[mi] = __builtin_amdgcn_mfma_f32_16x16x32_bf16(afrag, bfrag, acc[mi], 0, 0, 0); } }
;     const size_t trow = rowbase + 16 * w + fr; const float bias = bsp[g * 128 + 16 * w + fr];
; #pragma unroll
;     for (int mi = 0; mi < 8; ++mi) { const int c = 16 * mi + 4 * fq;
;         const f32x4 uv = unpack4(*(const u32x2*)(P0 + trow * AB_IN + 128 * g + c));
;         *(u32x2*)(MIX + trow * DM + 128 * g + c) = pack4((acc[mi] + bias) * uv); }
.LBB0_292:
	v_add_u32_e32 v35, 0, v33
	ds_read_b128 v[36:39], v35
	v_add_u32_e32 v35, 0, v32
	ds_read_b64_tr_b16 v[42:43], v35 offset:1088
	ds_read_b64_tr_b16 v[40:41], v35
	ds_read_b64_tr_b16 v[44:45], v35 offset:32
	ds_read_b64_tr_b16 v[46:47], v35 offset:1120
	v_add_u32_e32 v34, -1, v34
	s_waitcnt lgkmcnt(2)
	v_mfma_f32_16x16x32_bf16 v[28:31], v[40:43], v[36:39], v[28:31]
	ds_read_b64_tr_b16 v[40:41], v35 offset:64
	ds_read_b64_tr_b16 v[42:43], v35 offset:1152
	v_cmp_eq_u32_e32 vcc, 0, v34
	v_add_u32_e32 v33, 64, v33
	s_waitcnt lgkmcnt(0)
	v_mfma_f32_16x16x32_bf16 v[20:23], v[40:43], v[36:39], v[20:23]
	ds_read_b64_tr_b16 v[40:41], v35 offset:96
	ds_read_b64_tr_b16 v[42:43], v35 offset:1184
	v_add_u32_e32 v32, 0x2200, v32
	s_or_b64 s[0:1], vcc, s[0:1]
	s_waitcnt lgkmcnt(0)
	v_mfma_f32_16x16x32_bf16 v[16:19], v[40:43], v[36:39], v[16:19]
	ds_read_b64_tr_b16 v[40:41], v35 offset:128
	ds_read_b64_tr_b16 v[42:43], v35 offset:1216
	s_waitcnt lgkmcnt(0)
	v_mfma_f32_16x16x32_bf16 v[12:15], v[40:43], v[36:39], v[12:15]
	ds_read_b64_tr_b16 v[40:41], v35 offset:160
	ds_read_b64_tr_b16 v[42:43], v35 offset:1248
	s_waitcnt lgkmcnt(0)
	v_mfma_f32_16x16x32_bf16 v[8:11], v[40:43], v[36:39], v[8:11]
	ds_read_b64_tr_b16 v[40:41], v35 offset:192
	ds_read_b64_tr_b16 v[42:43], v35 offset:1280
	s_waitcnt lgkmcnt(0)
	v_mfma_f32_16x16x32_bf16 v[4:7], v[40:43], v[36:39], v[4:7]
	ds_read_b64_tr_b16 v[40:41], v35 offset:224
	ds_read_b64_tr_b16 v[42:43], v35 offset:1312
	v_mfma_f32_16x16x32_bf16 v[24:27], v[44:47], v[36:39], v[24:27]
	s_waitcnt lgkmcnt(0)
	v_mfma_f32_16x16x32_bf16 v[0:3], v[40:43], v[36:39], v[0:3]
	s_andn2_b64 exec, exec, s[0:1]
	s_cbranch_execnz .LBB0_292
	s_or_b64 exec, exec, s[0:1]
	v_add_u32_e32 v72, s5, v87
	v_mov_b64_e32 v[34:35], s[26:27]
	v_mad_u64_u32 v[34:35], s[0:1], v72, s3, v[34:35]
	s_lshl_b32 s22, s4, 1
	v_lshl_add_u64 v[34:35], v[34:35], 0, s[22:23]
	v_mov_b32_e32 v93, v73
	v_add_lshl_u32 v32, s4, v87, 2
	v_lshl_add_u64 v[34:35], v[34:35], 0, v[92:93]
	global_load_dword v32, v32, s[54:55]
	s_add_u32 s0, s40, s22
	global_load_dwordx2 v[38:39], v[34:35], off
	global_load_dwordx2 v[226:227], v[34:35], off offset:32
	global_load_dwordx2 v[228:229], v[34:35], off offset:64
	global_load_dwordx2 v[230:231], v[34:35], off offset:96
	global_load_dwordx2 v[232:233], v[34:35], off offset:128
	global_load_dwordx2 v[234:235], v[34:35], off offset:160
	global_load_dwordx2 v[236:237], v[34:35], off offset:192
	global_load_dwordx2 v[238:239], v[34:35], off offset:224
	s_addc_u32 s1, s41, 0
	v_lshlrev_b64 v[36:37], 11, v[72:73]
	v_lshl_add_u64 v[36:37], s[0:1], 0, v[36:37]
	s_mov_b64 s[0:1], 0
	s_waitcnt vmcnt(8)
	v_pk_add_f32 v[30:31], v[30:31], v[32:33] op_sel_hi:[1,0]
	v_pk_add_f32 v[28:29], v[28:29], v[32:33] op_sel_hi:[1,0]
	s_waitcnt vmcnt(7)
	v_lshlrev_b32_e32 v40, 16, v38
	v_and_b32_e32 v41, 0xffff0000, v38
	v_lshlrev_b32_e32 v38, 16, v39
	v_and_b32_e32 v39, 0xffff0000, v39
	v_pk_mul_f32 v[30:31], v[30:31], v[38:39]
	v_pk_mul_f32 v[28:29], v[28:29], v[40:41]
	v_cvt_pk_bf16_f32 v39, v30, v31
	v_cvt_pk_bf16_f32 v38, v28, v29
	v_lshl_add_u64 v[28:29], v[36:37], 0, v[92:93]
	v_pk_add_f32 v[24:25], v[24:25], v[32:33] op_sel_hi:[1,0]
	v_pk_add_f32 v[26:27], v[26:27], v[32:33] op_sel_hi:[1,0]
	v_pk_add_f32 v[20:21], v[20:21], v[32:33] op_sel_hi:[1,0]
	v_pk_add_f32 v[22:23], v[22:23], v[32:33] op_sel_hi:[1,0]
	v_pk_add_f32 v[16:17], v[16:17], v[32:33] op_sel_hi:[1,0]
	v_pk_add_f32 v[18:19], v[18:19], v[32:33] op_sel_hi:[1,0]
	v_pk_add_f32 v[12:13], v[12:13], v[32:33] op_sel_hi:[1,0]
	v_pk_add_f32 v[14:15], v[14:15], v[32:33] op_sel_hi:[1,0]
	v_pk_add_f32 v[8:9], v[8:9], v[32:33] op_sel_hi:[1,0]
	v_pk_add_f32 v[10:11], v[10:11], v[32:33] op_sel_hi:[1,0]
	v_pk_add_f32 v[4:5], v[4:5], v[32:33] op_sel_hi:[1,0]
	v_pk_add_f32 v[6:7], v[6:7], v[32:33] op_sel_hi:[1,0]
	v_pk_add_f32 v[0:1], v[0:1], v[32:33] op_sel_hi:[1,0]
	v_pk_add_f32 v[2:3], v[2:3], v[32:33] op_sel_hi:[1,0]
	global_store_dwordx2 v[28:29], v[38:39], off
	s_waitcnt vmcnt(7)
	v_mov_b32_e32 v30, v226
	v_mov_b32_e32 v31, v227
	v_lshlrev_b32_e32 v36, 16, v30
	v_and_b32_e32 v37, 0xffff0000, v30
	v_lshlrev_b32_e32 v30, 16, v31
	v_and_b32_e32 v31, 0xffff0000, v31
	v_pk_mul_f32 v[24:25], v[24:25], v[36:37]
	v_pk_mul_f32 v[26:27], v[26:27], v[30:31]
	v_cvt_pk_bf16_f32 v24, v24, v25
	s_nop 0
	v_cvt_pk_bf16_f32 v25, v26, v27
	global_store_dwordx2 v[28:29], v[24:25], off offset:32
	s_waitcnt vmcnt(7)
	v_mov_b32_e32 v24, v228
	v_mov_b32_e32 v25, v229
	v_lshlrev_b32_e32 v26, 16, v24
	v_and_b32_e32 v27, 0xffff0000, v24
	v_lshlrev_b32_e32 v24, 16, v25
	v_and_b32_e32 v25, 0xffff0000, v25
	v_pk_mul_f32 v[20:21], v[20:21], v[26:27]
	v_pk_mul_f32 v[22:23], v[22:23], v[24:25]
	v_cvt_pk_bf16_f32 v20, v20, v21
	s_nop 0
	v_cvt_pk_bf16_f32 v21, v22, v23
	global_store_dwordx2 v[28:29], v[20:21], off offset:64
	s_waitcnt vmcnt(7)
	v_mov_b32_e32 v20, v230
	v_mov_b32_e32 v21, v231
	v_lshlrev_b32_e32 v22, 16, v20
	v_and_b32_e32 v23, 0xffff0000, v20
	v_lshlrev_b32_e32 v20, 16, v21
	v_and_b32_e32 v21, 0xffff0000, v21
	v_pk_mul_f32 v[16:17], v[16:17], v[22:23]
	v_pk_mul_f32 v[18:19], v[18:19], v[20:21]
	v_cvt_pk_bf16_f32 v16, v16, v17
	s_nop 0
	v_cvt_pk_bf16_f32 v17, v18, v19
	global_store_dwordx2 v[28:29], v[16:17], off offset:96
	s_waitcnt vmcnt(7)
	v_mov_b32_e32 v16, v232
	v_mov_b32_e32 v17, v233
	v_lshlrev_b32_e32 v18, 16, v16
	v_and_b32_e32 v19, 0xffff0000, v16
	v_lshlrev_b32_e32 v16, 16, v17
	v_and_b32_e32 v17, 0xffff0000, v17
	v_pk_mul_f32 v[12:13], v[12:13], v[18:19]
	v_pk_mul_f32 v[14:15], v[14:15], v[16:17]
	v_cvt_pk_bf16_f32 v12, v12, v13
	s_nop 0
	v_cvt_pk_bf16_f32 v13, v14, v15
	global_store_dwordx2 v[28:29], v[12:13], off offset:128
	s_waitcnt vmcnt(7)
	v_mov_b32_e32 v12, v234
	v_mov_b32_e32 v13, v235
	v_lshlrev_b32_e32 v14, 16, v12
	v_and_b32_e32 v15, 0xffff0000, v12
	v_lshlrev_b32_e32 v12, 16, v13
	v_and_b32_e32 v13, 0xffff0000, v13
	v_pk_mul_f32 v[8:9], v[8:9], v[14:15]
	v_pk_mul_f32 v[10:11], v[10:11], v[12:13]
	v_cvt_pk_bf16_f32 v8, v8, v9
	s_nop 0
	v_cvt_pk_bf16_f32 v9, v10, v11
	global_store_dwordx2 v[28:29], v[8:9], off offset:160
	s_waitcnt vmcnt(7)
	v_mov_b32_e32 v8, v236
	v_mov_b32_e32 v9, v237
	v_lshlrev_b32_e32 v10, 16, v8
	v_and_b32_e32 v11, 0xffff0000, v8
	v_lshlrev_b32_e32 v8, 16, v9
	v_and_b32_e32 v9, 0xffff0000, v9
	v_pk_mul_f32 v[4:5], v[4:5], v[10:11]
	v_pk_mul_f32 v[6:7], v[6:7], v[8:9]
	v_cvt_pk_bf16_f32 v4, v4, v5
	s_nop 0
	v_cvt_pk_bf16_f32 v5, v6, v7
	global_store_dwordx2 v[28:29], v[4:5], off offset:192
	s_waitcnt vmcnt(7)
	v_mov_b32_e32 v4, v238
	v_mov_b32_e32 v5, v239
	v_lshlrev_b32_e32 v6, 16, v4
	v_and_b32_e32 v7, 0xffff0000, v4
	v_lshlrev_b32_e32 v4, 16, v5
	v_and_b32_e32 v5, 0xffff0000, v5
	v_pk_mul_f32 v[0:1], v[0:1], v[6:7]
	v_pk_mul_f32 v[2:3], v[2:3], v[4:5]
	v_cvt_pk_bf16_f32 v0, v0, v1
	s_nop 0
	v_cvt_pk_bf16_f32 v1, v2, v3
	global_store_dwordx2 v[28:29], v[0:1], off offset:224
